# short gated conv: second half-iteration's loads issued with the first half's (registers renamed), one global round trip per iteration hidden
# speedup vs baseline: 1.0070x; 1.0063x over previous
; __device__ __forceinline__ unsigned cvtpk(float lo, float hi) { f32x2_t v = {lo, hi}; bf16x2_t b = __builtin_convertvector(v, bf16x2_t); return __builtin_bit_cast(unsigned, b); }
; __device__ void conv_unit(LAS unsigned char* lds, const bf16_t* __restrict__ Z, bf16_t* __restrict__ MIX, int unit,
;                           const float* __restrict__ ccw, const float* __restrict__ ccb, const float* __restrict__ lng, const float* __restrict__ lnb, const float* __restrict__ scw) {
;     ...
;     for (int i = 0; i < 4; ++i) { const int id = tid + 512 * i, tok = id >> 5, c8 = (id & 31) * 8, tp = tpos0 + tok; const bf16_t* zr = Z + (size_t)(t0 + tok) * DIN + 2048 + c8;
;         u32x4 gcv[3], hsv[3];
; #pragma unroll
;         for (int k = 0; k < 3; ++k) { int back = 2 - k; back = (t0 + tok - back < 0) ? 0 : back; const bf16_t* zk = zr - (size_t)back * DIN; gcv[k] = *(const u32x4*)(zk + 256); hsv[k] = *(const u32x4*)(zk + 512); }
;         const u32x4 gb = *(const u32x4*)zr;
;         float y[8];
; #pragma unroll
;         for (int e = 0; e < 8; ++e) y[e] = 0.f;
; #pragma unroll
;         for (int k = 0; k < 3; ++k) { const u32x4 gc = gcv[k], hs = hsv[k]; const float on = (tp - 2 + k >= 0) ? 1.f : 0.f;
;                 const f32x4 w0 = *(const f32x4*)(scw + k * 256 + c8) * on, w1 = *(const f32x4*)(scw + k * 256 + c8 + 4) * on;
;                 y[0] += w0[0] * bflo(gc.x) * bflo(hs.x); y[1] += w0[1] * bfhi(gc.x) * bfhi(hs.x); y[2] += w0[2] * bflo(gc.y) * bflo(hs.y); y[3] += w0[3] * bfhi(gc.y) * bfhi(hs.y);
;                 y[4] += w1[0] * bflo(gc.z) * bflo(hs.z); y[5] += w1[1] * bfhi(gc.z) * bfhi(hs.z); y[6] += w1[2] * bflo(gc.w) * bflo(hs.w); y[7] += w1[3] * bfhi(gc.w) * bfhi(hs.w); }
;         u32x4 w;
;         w.x = cvtpk(bflo(gb.x) * y[0], bfhi(gb.x) * y[1]); w.y = cvtpk(bflo(gb.y) * y[2], bfhi(gb.y) * y[3]); w.z = cvtpk(bflo(gb.z) * y[4], bfhi(gb.z) * y[5]); w.w = cvtpk(bflo(gb.w) * y[6], bfhi(gb.w) * y[7]);
;         *(u32x4*)(MIX + (size_t)(t0 + tok) * DM + 768 + c8) = w; }
.LBB0_144:
	v_add_u32_e32 v86, s10, v100
	v_ashrrev_i32_e32 v60, 5, v86
	v_add_u32_e32 v56, s17, v60
	v_mov_b64_e32 v[58:59], s[20:21]
	v_mad_i64_i32 v[28:29], s[14:15], v56, s45, v[58:59]
	v_lshl_add_u64 v[52:53], v[28:29], 0, v[0:1]
	v_cmp_gt_i32_e32 vcc, 2, v56
	v_lshl_add_u64 v[48:49], v[52:53], 0, s[46:47]
	v_add_u32_e32 v76, s18, v60
	v_cndmask_b32_e64 v29, -1, 0, vcc
	v_cndmask_b32_e64 v28, v195, 0, vcc
	v_lshl_add_u64 v[32:33], v[48:49], 0, v[28:29]
	global_load_dwordx4 v[28:31], v[32:33], off offset:512
	s_nop 0
	global_load_dwordx4 v[32:35], v[32:33], off offset:1024
	v_cmp_lt_i32_e32 vcc, 0, v56
	v_ashrrev_i32_e32 v57, 31, v56
	s_addk_i32 s10, 0x400
	v_cndmask_b32_e64 v37, 0, -1, vcc
	v_cndmask_b32_e32 v36, 0, v196, vcc
	v_lshl_add_u64 v[40:41], v[48:49], 0, v[36:37]
	v_add_co_u32_e32 v52, vcc, s22, v52
	global_load_dwordx4 v[36:39], v[40:41], off offset:512
	s_nop 0
	global_load_dwordx4 v[40:43], v[40:41], off offset:1024
	s_nop 0
	global_load_dwordx4 v[44:47], v[48:49], off offset:512
	s_nop 0
	global_load_dwordx4 v[48:51], v[48:49], off offset:1024
	v_addc_co_u32_e32 v53, vcc, 0, v53, vcc
	global_load_dwordx4 v[52:55], v[52:53], off
	v_add_u32_e32 v108, 0x200, v86
	v_ashrrev_i32_e32 v140, 5, v108
	v_add_u32_e32 v136, s17, v140
	v_mad_i64_i32 v[108:109], s[14:15], v136, s45, v[58:59]
	v_lshl_add_u64 v[132:133], v[108:109], 0, v[0:1]
	v_cmp_gt_i32_e32 vcc, 2, v136
	v_lshl_add_u64 v[128:129], v[132:133], 0, s[46:47]
	v_add_u32_e32 v154, s18, v140
	v_cndmask_b32_e64 v109, -1, 0, vcc
	v_cndmask_b32_e64 v108, v195, 0, vcc
	v_lshl_add_u64 v[112:113], v[128:129], 0, v[108:109]
	global_load_dwordx4 v[108:111], v[112:113], off offset:512
	s_nop 0
	global_load_dwordx4 v[112:115], v[112:113], off offset:1024
	v_cmp_lt_i32_e32 vcc, 0, v136
	v_ashrrev_i32_e32 v137, 31, v136
	v_cndmask_b32_e64 v117, 0, -1, vcc
	v_cndmask_b32_e32 v116, 0, v196, vcc
	v_lshl_add_u64 v[120:121], v[128:129], 0, v[116:117]
	v_add_co_u32_e32 v132, vcc, s22, v132
	global_load_dwordx4 v[116:119], v[120:121], off offset:512
	s_nop 0
	global_load_dwordx4 v[120:123], v[120:121], off offset:1024
	s_nop 0
	global_load_dwordx4 v[124:127], v[128:129], off offset:512
	s_nop 0
	global_load_dwordx4 v[128:131], v[128:129], off offset:1024
	v_addc_co_u32_e32 v133, vcc, 0, v133, vcc
	global_load_dwordx4 v[132:135], v[132:133], off
	v_cmp_lt_i32_e32 vcc, 1, v76
	s_cmpk_lg_i32 s10, 0x800
	s_waitcnt vmcnt(13)
	v_lshlrev_b32_e32 v84, 16, v28
	v_cndmask_b32_e64 v60, 0, 1.0, vcc
	v_pk_mul_f32 v[64:65], v[6:7], v[60:61] op_sel_hi:[1,0]
	v_cmp_lt_i32_e32 vcc, 0, v76
	v_and_b32_e32 v85, 0xffff0000, v28
	v_pk_mul_f32 v[64:65], v[64:65], v[84:85]
	v_cndmask_b32_e64 v68, 0, 1.0, vcc
	s_waitcnt vmcnt(12)
	v_lshlrev_b32_e32 v84, 16, v32
	v_and_b32_e32 v85, 0xffff0000, v32
	v_pk_mul_f32 v[72:73], v[14:15], v[68:69] op_sel_hi:[1,0]
	v_cmp_lt_i32_e32 vcc, -1, v76
	v_pk_fma_f32 v[64:65], v[64:65], v[84:85], 0 op_sel_hi:[1,1,0]
	s_waitcnt vmcnt(11)
	v_lshlrev_b32_e32 v84, 16, v36
	v_and_b32_e32 v85, 0xffff0000, v36
	v_cndmask_b32_e64 v76, 0, 1.0, vcc
	v_pk_mul_f32 v[72:73], v[72:73], v[84:85]
	s_waitcnt vmcnt(10)
	v_lshlrev_b32_e32 v84, 16, v40
	v_and_b32_e32 v85, 0xffff0000, v40
	v_pk_mul_f32 v[80:81], v[22:23], v[76:77] op_sel_hi:[1,0]
	v_pk_fma_f32 v[64:65], v[72:73], v[84:85], v[64:65]
	s_waitcnt vmcnt(9)
	v_lshlrev_b32_e32 v72, 16, v44
	v_and_b32_e32 v73, 0xffff0000, v44
	v_pk_mul_f32 v[72:73], v[80:81], v[72:73]
	s_waitcnt vmcnt(8)
	v_lshlrev_b32_e32 v80, 16, v48
	v_and_b32_e32 v81, 0xffff0000, v48
	v_pk_fma_f32 v[64:65], v[72:73], v[80:81], v[64:65]
	s_waitcnt vmcnt(7)
	v_lshlrev_b32_e32 v72, 16, v52
	v_and_b32_e32 v73, 0xffff0000, v52
	v_pk_mul_f32 v[64:65], v[64:65], v[72:73]
	v_pk_mul_f32 v[62:63], v[8:9], v[60:61] op_sel_hi:[1,0]
	v_cvt_pk_bf16_f32 v28, v64, v65
	v_lshlrev_b32_e32 v64, 16, v29
	v_and_b32_e32 v65, 0xffff0000, v29
	v_pk_mul_f32 v[70:71], v[16:17], v[68:69] op_sel_hi:[1,0]
	v_pk_mul_f32 v[62:63], v[62:63], v[64:65]
	v_lshlrev_b32_e32 v32, 16, v33
	v_and_b32_e32 v33, 0xffff0000, v33
	v_lshlrev_b32_e32 v36, 16, v37
	v_and_b32_e32 v37, 0xffff0000, v37
	v_pk_fma_f32 v[32:33], v[62:63], v[32:33], 0 op_sel_hi:[1,1,0]
	v_pk_mul_f32 v[36:37], v[70:71], v[36:37]
	v_lshlrev_b32_e32 v40, 16, v41
	v_and_b32_e32 v41, 0xffff0000, v41
	v_pk_mul_f32 v[78:79], v[24:25], v[76:77] op_sel_hi:[1,0]
	v_pk_fma_f32 v[32:33], v[36:37], v[40:41], v[32:33]
	v_lshlrev_b32_e32 v36, 16, v45
	v_and_b32_e32 v37, 0xffff0000, v45
	v_pk_mul_f32 v[36:37], v[78:79], v[36:37]
	v_lshlrev_b32_e32 v40, 16, v49
	v_and_b32_e32 v41, 0xffff0000, v49
	v_pk_fma_f32 v[32:33], v[36:37], v[40:41], v[32:33]
	v_lshlrev_b32_e32 v36, 16, v53
	v_and_b32_e32 v37, 0xffff0000, v53
	v_pk_mul_f32 v[32:33], v[32:33], v[36:37]
	v_pk_mul_f32 v[66:67], v[4:5], v[60:61] op_sel_hi:[1,0]
	v_pk_mul_f32 v[60:61], v[2:3], v[60:61] op_sel_hi:[1,0]
	v_cvt_pk_bf16_f32 v29, v32, v33
	v_lshlrev_b32_e32 v32, 16, v30
	v_and_b32_e32 v33, 0xffff0000, v30
	v_pk_mul_f32 v[32:33], v[60:61], v[32:33]
	v_lshlrev_b32_e32 v36, 16, v34
	v_and_b32_e32 v37, 0xffff0000, v34
	v_pk_mul_f32 v[74:75], v[12:13], v[68:69] op_sel_hi:[1,0]
	v_pk_mul_f32 v[68:69], v[10:11], v[68:69] op_sel_hi:[1,0]
	v_pk_fma_f32 v[32:33], v[32:33], v[36:37], 0 op_sel_hi:[1,1,0]
	v_lshlrev_b32_e32 v36, 16, v38
	v_and_b32_e32 v37, 0xffff0000, v38
	v_pk_mul_f32 v[36:37], v[68:69], v[36:37]
	v_lshlrev_b32_e32 v40, 16, v42
	v_and_b32_e32 v41, 0xffff0000, v42
	v_pk_mul_f32 v[82:83], v[20:21], v[76:77] op_sel_hi:[1,0]
	v_pk_mul_f32 v[76:77], v[18:19], v[76:77] op_sel_hi:[1,0]
	v_pk_fma_f32 v[32:33], v[36:37], v[40:41], v[32:33]
	v_lshlrev_b32_e32 v36, 16, v46
	v_and_b32_e32 v37, 0xffff0000, v46
	v_pk_mul_f32 v[36:37], v[76:77], v[36:37]
	v_lshlrev_b32_e32 v40, 16, v50
	v_and_b32_e32 v41, 0xffff0000, v50
	v_pk_fma_f32 v[32:33], v[36:37], v[40:41], v[32:33]
	v_lshlrev_b32_e32 v36, 16, v54
	v_and_b32_e32 v37, 0xffff0000, v54
	v_pk_mul_f32 v[32:33], v[32:33], v[36:37]
	v_lshlrev_b32_e32 v34, 16, v35
	v_cvt_pk_bf16_f32 v30, v32, v33
	v_lshlrev_b32_e32 v32, 16, v31
	v_and_b32_e32 v33, 0xffff0000, v31
	v_pk_mul_f32 v[32:33], v[66:67], v[32:33]
	v_and_b32_e32 v35, 0xffff0000, v35
	v_pk_fma_f32 v[32:33], v[32:33], v[34:35], 0 op_sel_hi:[1,1,0]
	v_lshlrev_b32_e32 v34, 16, v39
	v_and_b32_e32 v35, 0xffff0000, v39
	v_pk_mul_f32 v[34:35], v[74:75], v[34:35]
	v_lshlrev_b32_e32 v36, 16, v43
	v_and_b32_e32 v37, 0xffff0000, v43
	v_pk_fma_f32 v[32:33], v[34:35], v[36:37], v[32:33]
	v_lshlrev_b32_e32 v34, 16, v47
	v_and_b32_e32 v35, 0xffff0000, v47
	v_pk_mul_f32 v[34:35], v[82:83], v[34:35]
	v_lshlrev_b32_e32 v36, 16, v51
	v_and_b32_e32 v37, 0xffff0000, v51
	v_pk_fma_f32 v[32:33], v[34:35], v[36:37], v[32:33]
	v_lshlrev_b32_e32 v34, 16, v55
	v_and_b32_e32 v35, 0xffff0000, v55
	v_pk_mul_f32 v[32:33], v[32:33], v[34:35]
	s_nop 0
	v_cvt_pk_bf16_f32 v31, v32, v33
	v_lshlrev_b64 v[32:33], 11, v[56:57]
	v_lshl_add_u64 v[32:33], v[26:27], 0, v[32:33]
	global_store_dwordx4 v[32:33], v[28:31], off offset:1536
	s_nop 1
	s_waitcnt vmcnt(7)
; __device__ __forceinline__ int bid_opq() { int b = blockIdx.x; asm volatile("" : "+s"(b)); return b; }
; __device__ void conv_unit(LAS unsigned char* lds, const bf16_t* __restrict__ Z, bf16_t* __restrict__ MIX, int unit,
;                           const float* __restrict__ ccw, const float* __restrict__ ccb, const float* __restrict__ lng, const float* __restrict__ lnb, const float* __restrict__ scw) {
;     ...
;     for (int i = 0; i < 4; ++i) { const int id = tid + 512 * i, tok = id >> 5, c8 = (id & 31) * 8, tp = tpos0 + tok; const bf16_t* zr = Z + (size_t)(t0 + tok) * DIN + 2048 + c8;
;         u32x4 gcv[3], hsv[3];
; #pragma unroll
;         for (int k = 0; k < 3; ++k) { int back = 2 - k; back = (t0 + tok - back < 0) ? 0 : back; const bf16_t* zk = zr - (size_t)back * DIN; gcv[k] = *(const u32x4*)(zk + 256); hsv[k] = *(const u32x4*)(zk + 512); }
;         const u32x4 gb = *(const u32x4*)zr;
;         float y[8];
; #pragma unroll
;         for (int e = 0; e < 8; ++e) y[e] = 0.f;
; #pragma unroll
;         for (int k = 0; k < 3; ++k) { const u32x4 gc = gcv[k], hs = hsv[k]; const float on = (tp - 2 + k >= 0) ? 1.f : 0.f;
;                 const f32x4 w0 = *(const f32x4*)(scw + k * 256 + c8) * on, w1 = *(const f32x4*)(scw + k * 256 + c8 + 4) * on;
;                 y[0] += w0[0] * bflo(gc.x) * bflo(hs.x); y[1] += w0[1] * bfhi(gc.x) * bfhi(hs.x); y[2] += w0[2] * bflo(gc.y) * bflo(hs.y); y[3] += w0[3] * bfhi(gc.y) * bfhi(hs.y);
;                 y[4] += w1[0] * bflo(gc.z) * bflo(hs.z); y[5] += w1[1] * bfhi(gc.z) * bfhi(hs.z); y[6] += w1[2] * bflo(gc.w) * bflo(hs.w); y[7] += w1[3] * bfhi(gc.w) * bfhi(hs.w); }
;         u32x4 w;
;         w.x = cvtpk(bflo(gb.x) * y[0], bfhi(gb.x) * y[1]); w.y = cvtpk(bflo(gb.y) * y[2], bfhi(gb.y) * y[3]); w.z = cvtpk(bflo(gb.z) * y[4], bfhi(gb.z) * y[5]); w.w = cvtpk(bflo(gb.w) * y[6], bfhi(gb.w) * y[7]);
;         *(u32x4*)(MIX + (size_t)(t0 + tok) * DM + 768 + c8) = w; }
; __device__ __forceinline__ void run_phase(const Params& p, LAS unsigned char* lds, int ph, bool dummy) {
;     ...
;         for (int u = bid_opq(); u < MTOK / 64; u += gridDim.x) conv_unit(lds, Z, XB1, u, p.in[13] + l * 31 * 256, p.in[14] + l * 256, p.in[15] + l * 256, p.in[16] + l * 256, p.in[17] + l * 3 * 256);
	v_lshlrev_b32_e32 v162, 16, v108
	v_cmp_lt_i32_e32 vcc, 1, v154
	v_and_b32_e32 v163, 0xffff0000, v108
	s_nop 0
	v_cndmask_b32_e64 v138, 0, 1.0, vcc
	v_pk_mul_f32 v[142:143], v[6:7], v[138:139] op_sel_hi:[1,0]
	v_cmp_lt_i32_e32 vcc, 0, v154
	v_pk_mul_f32 v[142:143], v[142:143], v[162:163]
	s_waitcnt vmcnt(6)
	v_lshlrev_b32_e32 v162, 16, v112
	v_cndmask_b32_e64 v146, 0, 1.0, vcc
	v_and_b32_e32 v163, 0xffff0000, v112
	v_pk_mul_f32 v[150:151], v[14:15], v[146:147] op_sel_hi:[1,0]
	v_cmp_lt_i32_e32 vcc, -1, v154
	v_pk_fma_f32 v[142:143], v[142:143], v[162:163], 0 op_sel_hi:[1,1,0]
	v_pk_mul_f32 v[140:141], v[8:9], v[138:139] op_sel_hi:[1,0]
	v_cndmask_b32_e64 v154, 0, 1.0, vcc
	v_pk_mul_f32 v[158:159], v[22:23], v[154:155] op_sel_hi:[1,0]
	v_pk_mul_f32 v[148:149], v[16:17], v[146:147] op_sel_hi:[1,0]
	v_lshlrev_b32_e32 v112, 16, v113
	v_and_b32_e32 v113, 0xffff0000, v113
	v_pk_mul_f32 v[156:157], v[24:25], v[154:155] op_sel_hi:[1,0]
	v_pk_mul_f32 v[144:145], v[4:5], v[138:139] op_sel_hi:[1,0]
	v_pk_mul_f32 v[138:139], v[2:3], v[138:139] op_sel_hi:[1,0]
	v_pk_mul_f32 v[152:153], v[12:13], v[146:147] op_sel_hi:[1,0]
	v_pk_mul_f32 v[146:147], v[10:11], v[146:147] op_sel_hi:[1,0]
	v_pk_mul_f32 v[160:161], v[20:21], v[154:155] op_sel_hi:[1,0]
	v_pk_mul_f32 v[154:155], v[18:19], v[154:155] op_sel_hi:[1,0]
	s_waitcnt vmcnt(5)
	v_lshlrev_b32_e32 v162, 16, v116
	v_and_b32_e32 v163, 0xffff0000, v116
	v_pk_mul_f32 v[150:151], v[150:151], v[162:163]
	s_waitcnt vmcnt(4)
	v_lshlrev_b32_e32 v162, 16, v120
	v_and_b32_e32 v163, 0xffff0000, v120
	v_pk_fma_f32 v[142:143], v[150:151], v[162:163], v[142:143]
	s_waitcnt vmcnt(3)
	v_lshlrev_b32_e32 v150, 16, v124
	v_and_b32_e32 v151, 0xffff0000, v124
	v_pk_mul_f32 v[150:151], v[158:159], v[150:151]
	s_waitcnt vmcnt(2)
	v_lshlrev_b32_e32 v158, 16, v128
	v_and_b32_e32 v159, 0xffff0000, v128
	v_pk_fma_f32 v[142:143], v[150:151], v[158:159], v[142:143]
	s_waitcnt vmcnt(1)
	v_lshlrev_b32_e32 v150, 16, v132
	v_and_b32_e32 v151, 0xffff0000, v132
	v_pk_mul_f32 v[142:143], v[142:143], v[150:151]
	v_lshlrev_b32_e32 v116, 16, v117
	v_cvt_pk_bf16_f32 v108, v142, v143
	v_lshlrev_b32_e32 v142, 16, v109
	v_and_b32_e32 v143, 0xffff0000, v109
	v_pk_mul_f32 v[140:141], v[140:141], v[142:143]
	v_and_b32_e32 v117, 0xffff0000, v117
	v_pk_fma_f32 v[112:113], v[140:141], v[112:113], 0 op_sel_hi:[1,1,0]
	v_pk_mul_f32 v[116:117], v[148:149], v[116:117]
	v_lshlrev_b32_e32 v120, 16, v121
	v_and_b32_e32 v121, 0xffff0000, v121
	v_pk_fma_f32 v[112:113], v[116:117], v[120:121], v[112:113]
	v_lshlrev_b32_e32 v116, 16, v125
	v_and_b32_e32 v117, 0xffff0000, v125
	v_pk_mul_f32 v[116:117], v[156:157], v[116:117]
	v_lshlrev_b32_e32 v120, 16, v129
	v_and_b32_e32 v121, 0xffff0000, v129
	v_pk_fma_f32 v[112:113], v[116:117], v[120:121], v[112:113]
	v_lshlrev_b32_e32 v116, 16, v133
	v_and_b32_e32 v117, 0xffff0000, v133
	v_pk_mul_f32 v[112:113], v[112:113], v[116:117]
	v_lshlrev_b32_e32 v116, 16, v114
	v_cvt_pk_bf16_f32 v109, v112, v113
	v_lshlrev_b32_e32 v112, 16, v110
	v_and_b32_e32 v113, 0xffff0000, v110
	v_pk_mul_f32 v[112:113], v[138:139], v[112:113]
	v_and_b32_e32 v117, 0xffff0000, v114
	v_pk_fma_f32 v[112:113], v[112:113], v[116:117], 0 op_sel_hi:[1,1,0]
	v_lshlrev_b32_e32 v116, 16, v118
	v_and_b32_e32 v117, 0xffff0000, v118
	v_pk_mul_f32 v[116:117], v[146:147], v[116:117]
	v_lshlrev_b32_e32 v120, 16, v122
	v_and_b32_e32 v121, 0xffff0000, v122
	v_pk_fma_f32 v[112:113], v[116:117], v[120:121], v[112:113]
	v_lshlrev_b32_e32 v116, 16, v126
	v_and_b32_e32 v117, 0xffff0000, v126
	v_pk_mul_f32 v[116:117], v[154:155], v[116:117]
	v_lshlrev_b32_e32 v120, 16, v130
	v_and_b32_e32 v121, 0xffff0000, v130
	v_pk_fma_f32 v[112:113], v[116:117], v[120:121], v[112:113]
	v_lshlrev_b32_e32 v116, 16, v134
	v_and_b32_e32 v117, 0xffff0000, v134
	v_pk_mul_f32 v[112:113], v[112:113], v[116:117]
	v_lshlrev_b32_e32 v114, 16, v115
	v_cvt_pk_bf16_f32 v110, v112, v113
	v_lshlrev_b32_e32 v112, 16, v111
	v_and_b32_e32 v113, 0xffff0000, v111
	v_pk_mul_f32 v[112:113], v[144:145], v[112:113]
	v_and_b32_e32 v115, 0xffff0000, v115
	v_pk_fma_f32 v[112:113], v[112:113], v[114:115], 0 op_sel_hi:[1,1,0]
	v_lshlrev_b32_e32 v114, 16, v119
	v_and_b32_e32 v115, 0xffff0000, v119
	v_pk_mul_f32 v[114:115], v[152:153], v[114:115]
	v_lshlrev_b32_e32 v116, 16, v123
	v_and_b32_e32 v117, 0xffff0000, v123
	v_pk_fma_f32 v[112:113], v[114:115], v[116:117], v[112:113]
	v_lshlrev_b32_e32 v114, 16, v127
	v_and_b32_e32 v115, 0xffff0000, v127
	v_pk_mul_f32 v[114:115], v[160:161], v[114:115]
	v_lshlrev_b32_e32 v116, 16, v131
	v_and_b32_e32 v117, 0xffff0000, v131
	v_pk_fma_f32 v[112:113], v[114:115], v[116:117], v[112:113]
	v_lshlrev_b32_e32 v114, 16, v135
	v_and_b32_e32 v115, 0xffff0000, v135
	v_pk_mul_f32 v[112:113], v[112:113], v[114:115]
	s_nop 0
	v_cvt_pk_bf16_f32 v111, v112, v113
	v_lshlrev_b64 v[112:113], 11, v[136:137]
	v_lshl_add_u64 v[112:113], v[26:27], 0, v[112:113]
	global_store_dwordx4 v[112:113], v[108:111], off offset:1536
	s_cbranch_scc1 .LBB0_144
	s_add_i32 s16, s16, s34
	s_cmpk_gt_i32 s16, 0xff
	s_cbranch_scc0 .LBB0_127
